# c26: SSD pass-3 entering-state prefix software-pipelined (next segment's nine loads in flight during this segment's FMAs)
# baseline (speedup 1.0000x reference)
; template <int PASS>
; __device__ void ssd_item(const Params& p, int item, int l, unsigned char* smem) {
;     ...
;             for (int e = NSEG - 1; e > seg; --e) { const float dc = __expf(SEGT[ibase + e]); const f32x4* src = (const f32x4*)(ST + (size_t)(ibase + e) * 8192);
; #pragma unroll
;                 for (int nt = 0; nt < 8; ++nt) S[nt] = S[nt] * dc + src[(w * 8 + nt) * 64 + lane]; }
;         }
.LBB0_860:
	s_add_u32 s26, s92, s22
	s_addc_u32 s27, s93, s23
	global_load_dword v162, v81, s[26:27]
	s_mov_b32 s25, 0x1b078000
	s_add_i32 s24, s24, -1
	s_add_u32 s22, s22, -4
	s_movk_i32 s26, 0x8000
	s_addc_u32 s23, s23, -1
	s_mov_b32 s27, -1
	s_cmp_gt_u32 s24, s12
	s_cselect_b32 s98, 1, 0
	v_lshl_add_u64 v[38:39], s[92:93], 0, v[34:35]
	v_add_co_u32_e32 v44, vcc, s25, v38
	s_mov_b32 s25, 0x1b079000
	s_nop 0
	v_addc_co_u32_e32 v45, vcc, 0, v39, vcc
	v_add_co_u32_e32 v46, vcc, s25, v38
	v_lshl_add_u64 v[34:35], v[34:35], 0, s[26:27]
	s_nop 0
	v_addc_co_u32_e32 v47, vcc, 0, v39, vcc
	global_load_dwordx4 v[120:123], v[46:47], off offset:-4096
	global_load_dwordx4 v[124:127], v[44:45], off offset:1024
	global_load_dwordx4 v[128:131], v[44:45], off offset:2048
	global_load_dwordx4 v[132:135], v[44:45], off offset:3072
	global_load_dwordx4 v[136:139], v[46:47], off
	global_load_dwordx4 v[140:143], v[46:47], off offset:1024
	global_load_dwordx4 v[144:147], v[46:47], off offset:2048
	global_load_dwordx4 v[148:151], v[46:47], off offset:3072
.Lpfb_loop:
	s_cmp_lg_u32 s98, 0
	s_cbranch_scc0 .Lpfb_lastA
	s_add_u32 s26, s92, s22
	s_addc_u32 s27, s93, s23
	global_load_dword v206, v81, s[26:27]
	s_mov_b32 s25, 0x1b078000
	s_add_i32 s24, s24, -1
	s_add_u32 s22, s22, -4
	s_movk_i32 s26, 0x8000
	s_addc_u32 s23, s23, -1
	s_mov_b32 s27, -1
	s_cmp_gt_u32 s24, s12
	s_cselect_b32 s98, 1, 0
	v_lshl_add_u64 v[38:39], s[92:93], 0, v[34:35]
	v_add_co_u32_e32 v44, vcc, s25, v38
	s_mov_b32 s25, 0x1b079000
	s_nop 0
	v_addc_co_u32_e32 v45, vcc, 0, v39, vcc
	v_add_co_u32_e32 v46, vcc, s25, v38
	v_lshl_add_u64 v[34:35], v[34:35], 0, s[26:27]
	s_nop 0
	v_addc_co_u32_e32 v47, vcc, 0, v39, vcc
	global_load_dwordx4 v[190:193], v[46:47], off offset:-4096
	global_load_dwordx4 v[194:197], v[44:45], off offset:1024
	global_load_dwordx4 v[198:201], v[44:45], off offset:2048
	global_load_dwordx4 v[202:205], v[44:45], off offset:3072
	global_load_dwordx4 v[236:239], v[46:47], off
	global_load_dwordx4 v[240:243], v[46:47], off offset:1024
	global_load_dwordx4 v[244:247], v[46:47], off offset:2048
	global_load_dwordx4 v[248:251], v[46:47], off offset:3072
	s_waitcnt vmcnt(17)
	v_mul_f32_e32 v162, 0x3fb8aa3b, v162
	v_exp_f32_e32 v42, v162
	s_waitcnt vmcnt(9)
	v_pk_fma_f32 v[2:3], v[2:3], v[42:43], v[122:123] op_sel_hi:[1,0,1]
	v_pk_fma_f32 v[0:1], v[0:1], v[42:43], v[120:121] op_sel_hi:[1,0,1]
	v_pk_fma_f32 v[6:7], v[6:7], v[42:43], v[126:127] op_sel_hi:[1,0,1]
	v_pk_fma_f32 v[4:5], v[4:5], v[42:43], v[124:125] op_sel_hi:[1,0,1]
	v_pk_fma_f32 v[10:11], v[10:11], v[42:43], v[130:131] op_sel_hi:[1,0,1]
	v_pk_fma_f32 v[8:9], v[8:9], v[42:43], v[128:129] op_sel_hi:[1,0,1]
	v_pk_fma_f32 v[14:15], v[14:15], v[42:43], v[134:135] op_sel_hi:[1,0,1]
	v_pk_fma_f32 v[12:13], v[12:13], v[42:43], v[132:133] op_sel_hi:[1,0,1]
	v_pk_fma_f32 v[18:19], v[18:19], v[42:43], v[138:139] op_sel_hi:[1,0,1]
	v_pk_fma_f32 v[16:17], v[16:17], v[42:43], v[136:137] op_sel_hi:[1,0,1]
	v_pk_fma_f32 v[22:23], v[22:23], v[42:43], v[142:143] op_sel_hi:[1,0,1]
	v_pk_fma_f32 v[20:21], v[20:21], v[42:43], v[140:141] op_sel_hi:[1,0,1]
	v_pk_fma_f32 v[26:27], v[26:27], v[42:43], v[146:147] op_sel_hi:[1,0,1]
	v_pk_fma_f32 v[24:25], v[24:25], v[42:43], v[144:145] op_sel_hi:[1,0,1]
	v_pk_fma_f32 v[30:31], v[30:31], v[42:43], v[150:151] op_sel_hi:[1,0,1]
	v_pk_fma_f32 v[28:29], v[28:29], v[42:43], v[148:149] op_sel_hi:[1,0,1]
	s_cmp_lg_u32 s98, 0
	s_cbranch_scc0 .Lpfb_lastB
	s_add_u32 s26, s92, s22
	s_addc_u32 s27, s93, s23
	global_load_dword v162, v81, s[26:27]
	s_mov_b32 s25, 0x1b078000
	s_add_i32 s24, s24, -1
	s_add_u32 s22, s22, -4
	s_movk_i32 s26, 0x8000
	s_addc_u32 s23, s23, -1
	s_mov_b32 s27, -1
	s_cmp_gt_u32 s24, s12
	s_cselect_b32 s98, 1, 0
	v_lshl_add_u64 v[38:39], s[92:93], 0, v[34:35]
	v_add_co_u32_e32 v44, vcc, s25, v38
	s_mov_b32 s25, 0x1b079000
	s_nop 0
	v_addc_co_u32_e32 v45, vcc, 0, v39, vcc
	v_add_co_u32_e32 v46, vcc, s25, v38
	v_lshl_add_u64 v[34:35], v[34:35], 0, s[26:27]
	s_nop 0
	v_addc_co_u32_e32 v47, vcc, 0, v39, vcc
	global_load_dwordx4 v[120:123], v[46:47], off offset:-4096
	global_load_dwordx4 v[124:127], v[44:45], off offset:1024
	global_load_dwordx4 v[128:131], v[44:45], off offset:2048
	global_load_dwordx4 v[132:135], v[44:45], off offset:3072
	global_load_dwordx4 v[136:139], v[46:47], off
	global_load_dwordx4 v[140:143], v[46:47], off offset:1024
	global_load_dwordx4 v[144:147], v[46:47], off offset:2048
	global_load_dwordx4 v[148:151], v[46:47], off offset:3072
	s_waitcnt vmcnt(17)
	v_mul_f32_e32 v206, 0x3fb8aa3b, v206
	v_exp_f32_e32 v42, v206
	s_waitcnt vmcnt(9)
	v_pk_fma_f32 v[2:3], v[2:3], v[42:43], v[192:193] op_sel_hi:[1,0,1]
	v_pk_fma_f32 v[0:1], v[0:1], v[42:43], v[190:191] op_sel_hi:[1,0,1]
	v_pk_fma_f32 v[6:7], v[6:7], v[42:43], v[196:197] op_sel_hi:[1,0,1]
	v_pk_fma_f32 v[4:5], v[4:5], v[42:43], v[194:195] op_sel_hi:[1,0,1]
	v_pk_fma_f32 v[10:11], v[10:11], v[42:43], v[200:201] op_sel_hi:[1,0,1]
	v_pk_fma_f32 v[8:9], v[8:9], v[42:43], v[198:199] op_sel_hi:[1,0,1]
	v_pk_fma_f32 v[14:15], v[14:15], v[42:43], v[204:205] op_sel_hi:[1,0,1]
	v_pk_fma_f32 v[12:13], v[12:13], v[42:43], v[202:203] op_sel_hi:[1,0,1]
	v_pk_fma_f32 v[18:19], v[18:19], v[42:43], v[238:239] op_sel_hi:[1,0,1]
	v_pk_fma_f32 v[16:17], v[16:17], v[42:43], v[236:237] op_sel_hi:[1,0,1]
	v_pk_fma_f32 v[22:23], v[22:23], v[42:43], v[242:243] op_sel_hi:[1,0,1]
	v_pk_fma_f32 v[20:21], v[20:21], v[42:43], v[240:241] op_sel_hi:[1,0,1]
	v_pk_fma_f32 v[26:27], v[26:27], v[42:43], v[246:247] op_sel_hi:[1,0,1]
	v_pk_fma_f32 v[24:25], v[24:25], v[42:43], v[244:245] op_sel_hi:[1,0,1]
	v_pk_fma_f32 v[30:31], v[30:31], v[42:43], v[250:251] op_sel_hi:[1,0,1]
	v_pk_fma_f32 v[28:29], v[28:29], v[42:43], v[248:249] op_sel_hi:[1,0,1]
	s_branch .Lpfb_loop
; template <int PASS>
; __device__ void ssd_item(const Params& p, int item, int l, unsigned char* smem) {
;     ...
;             for (int e = NSEG - 1; e > seg; --e) { const float dc = __expf(SEGT[ibase + e]); const f32x4* src = (const f32x4*)(ST + (size_t)(ibase + e) * 8192);
; #pragma unroll
;                 for (int nt = 0; nt < 8; ++nt) S[nt] = S[nt] * dc + src[(w * 8 + nt) * 64 + lane]; }
;         }
.Lpfb_lastA:
	s_waitcnt vmcnt(8)
	v_mul_f32_e32 v162, 0x3fb8aa3b, v162
	v_exp_f32_e32 v42, v162
	s_waitcnt vmcnt(0)
	v_pk_fma_f32 v[2:3], v[2:3], v[42:43], v[122:123] op_sel_hi:[1,0,1]
	v_pk_fma_f32 v[0:1], v[0:1], v[42:43], v[120:121] op_sel_hi:[1,0,1]
	v_pk_fma_f32 v[6:7], v[6:7], v[42:43], v[126:127] op_sel_hi:[1,0,1]
	v_pk_fma_f32 v[4:5], v[4:5], v[42:43], v[124:125] op_sel_hi:[1,0,1]
	v_pk_fma_f32 v[10:11], v[10:11], v[42:43], v[130:131] op_sel_hi:[1,0,1]
	v_pk_fma_f32 v[8:9], v[8:9], v[42:43], v[128:129] op_sel_hi:[1,0,1]
	v_pk_fma_f32 v[14:15], v[14:15], v[42:43], v[134:135] op_sel_hi:[1,0,1]
	v_pk_fma_f32 v[12:13], v[12:13], v[42:43], v[132:133] op_sel_hi:[1,0,1]
	v_pk_fma_f32 v[18:19], v[18:19], v[42:43], v[138:139] op_sel_hi:[1,0,1]
	v_pk_fma_f32 v[16:17], v[16:17], v[42:43], v[136:137] op_sel_hi:[1,0,1]
	v_pk_fma_f32 v[22:23], v[22:23], v[42:43], v[142:143] op_sel_hi:[1,0,1]
	v_pk_fma_f32 v[20:21], v[20:21], v[42:43], v[140:141] op_sel_hi:[1,0,1]
	v_pk_fma_f32 v[26:27], v[26:27], v[42:43], v[146:147] op_sel_hi:[1,0,1]
	v_pk_fma_f32 v[24:25], v[24:25], v[42:43], v[144:145] op_sel_hi:[1,0,1]
	v_pk_fma_f32 v[30:31], v[30:31], v[42:43], v[150:151] op_sel_hi:[1,0,1]
	v_pk_fma_f32 v[28:29], v[28:29], v[42:43], v[148:149] op_sel_hi:[1,0,1]
	s_branch .Lpfb_done
.Lpfb_lastB:
	s_waitcnt vmcnt(8)
	v_mul_f32_e32 v206, 0x3fb8aa3b, v206
	v_exp_f32_e32 v42, v206
	s_waitcnt vmcnt(0)
	v_pk_fma_f32 v[2:3], v[2:3], v[42:43], v[192:193] op_sel_hi:[1,0,1]
	v_pk_fma_f32 v[0:1], v[0:1], v[42:43], v[190:191] op_sel_hi:[1,0,1]
	v_pk_fma_f32 v[6:7], v[6:7], v[42:43], v[196:197] op_sel_hi:[1,0,1]
	v_pk_fma_f32 v[4:5], v[4:5], v[42:43], v[194:195] op_sel_hi:[1,0,1]
	v_pk_fma_f32 v[10:11], v[10:11], v[42:43], v[200:201] op_sel_hi:[1,0,1]
	v_pk_fma_f32 v[8:9], v[8:9], v[42:43], v[198:199] op_sel_hi:[1,0,1]
	v_pk_fma_f32 v[14:15], v[14:15], v[42:43], v[204:205] op_sel_hi:[1,0,1]
	v_pk_fma_f32 v[12:13], v[12:13], v[42:43], v[202:203] op_sel_hi:[1,0,1]
	v_pk_fma_f32 v[18:19], v[18:19], v[42:43], v[238:239] op_sel_hi:[1,0,1]
	v_pk_fma_f32 v[16:17], v[16:17], v[42:43], v[236:237] op_sel_hi:[1,0,1]
	v_pk_fma_f32 v[22:23], v[22:23], v[42:43], v[242:243] op_sel_hi:[1,0,1]
	v_pk_fma_f32 v[20:21], v[20:21], v[42:43], v[240:241] op_sel_hi:[1,0,1]
	v_pk_fma_f32 v[26:27], v[26:27], v[42:43], v[246:247] op_sel_hi:[1,0,1]
	v_pk_fma_f32 v[24:25], v[24:25], v[42:43], v[244:245] op_sel_hi:[1,0,1]
	v_pk_fma_f32 v[30:31], v[30:31], v[42:43], v[250:251] op_sel_hi:[1,0,1]
	v_pk_fma_f32 v[28:29], v[28:29], v[42:43], v[248:249] op_sel_hi:[1,0,1]
.Lpfb_done:
	s_mov_b64 s[42:43], 0

; template <int PASS>
; __device__ void ssd_item(const Params& p, int item, int l, unsigned char* smem) {
;     ...
;         if (dir == 0) {
;             for (int e = 0; e < seg; ++e) { const float dc = __expf(SEGT[ibase + e]); const f32x4* src = (const f32x4*)(ST + (size_t)(ibase + e) * 8192);
; #pragma unroll
;                 for (int nt = 0; nt < 8; ++nt) S[nt] = S[nt] * dc + src[(w * 8 + nt) * 64 + lane]; }
;         } else {
;             for (int e = NSEG - 1; e > seg; --e) { const float dc = __expf(SEGT[ibase + e]); const f32x4* src = (const f32x4*)(ST + (size_t)(ibase + e) * 8192);
; #pragma unroll
;                 for (int nt = 0; nt < 8; ++nt) S[nt] = S[nt] * dc + src[(w * 8 + nt) * 64 + lane]; }
;         }
.LBB0_865:
	s_add_u32 s26, s92, s23
	s_addc_u32 s27, s93, s24
	global_load_dword v162, v81, s[26:27]
	s_mov_b32 s25, 0x1b000000
	s_add_i32 s22, s22, -1
	s_add_u32 s23, s23, 4
	s_addc_u32 s24, s24, 0
	s_cmp_eq_u32 s22, 0
	s_cselect_b32 s98, 0, 1
	v_lshl_add_u64 v[38:39], s[92:93], 0, v[34:35]
	v_add_co_u32_e32 v44, vcc, s25, v38
	s_mov_b32 s25, 0x1b001000
	s_nop 0
	v_addc_co_u32_e32 v45, vcc, 0, v39, vcc
	v_add_co_u32_e32 v46, vcc, s25, v38
	v_lshl_add_u64 v[34:35], v[34:35], 0, s[14:15]
	s_nop 0
	v_addc_co_u32_e32 v47, vcc, 0, v39, vcc
	global_load_dwordx4 v[120:123], v[46:47], off offset:-4096
	global_load_dwordx4 v[124:127], v[44:45], off offset:1024
	global_load_dwordx4 v[128:131], v[44:45], off offset:2048
	global_load_dwordx4 v[132:135], v[44:45], off offset:3072
	global_load_dwordx4 v[136:139], v[46:47], off
	global_load_dwordx4 v[140:143], v[46:47], off offset:1024
	global_load_dwordx4 v[144:147], v[46:47], off offset:2048
	global_load_dwordx4 v[148:151], v[46:47], off offset:3072
.Lpff_loop:
	s_cmp_lg_u32 s98, 0
	s_cbranch_scc0 .Lpff_lastA
	s_add_u32 s26, s92, s23
	s_addc_u32 s27, s93, s24
	global_load_dword v206, v81, s[26:27]
	s_mov_b32 s25, 0x1b000000
	s_add_i32 s22, s22, -1
	s_add_u32 s23, s23, 4
	s_addc_u32 s24, s24, 0
	s_cmp_eq_u32 s22, 0
	s_cselect_b32 s98, 0, 1
	v_lshl_add_u64 v[38:39], s[92:93], 0, v[34:35]
	v_add_co_u32_e32 v44, vcc, s25, v38
	s_mov_b32 s25, 0x1b001000
	s_nop 0
	v_addc_co_u32_e32 v45, vcc, 0, v39, vcc
	v_add_co_u32_e32 v46, vcc, s25, v38
	v_lshl_add_u64 v[34:35], v[34:35], 0, s[14:15]
	s_nop 0
	v_addc_co_u32_e32 v47, vcc, 0, v39, vcc
	global_load_dwordx4 v[190:193], v[46:47], off offset:-4096
	global_load_dwordx4 v[194:197], v[44:45], off offset:1024
	global_load_dwordx4 v[198:201], v[44:45], off offset:2048
	global_load_dwordx4 v[202:205], v[44:45], off offset:3072
	global_load_dwordx4 v[236:239], v[46:47], off
	global_load_dwordx4 v[240:243], v[46:47], off offset:1024
	global_load_dwordx4 v[244:247], v[46:47], off offset:2048
	global_load_dwordx4 v[248:251], v[46:47], off offset:3072
	s_waitcnt vmcnt(17)
	v_mul_f32_e32 v162, 0x3fb8aa3b, v162
	v_exp_f32_e32 v42, v162
	s_waitcnt vmcnt(9)
	v_pk_fma_f32 v[2:3], v[2:3], v[42:43], v[122:123] op_sel_hi:[1,0,1]
	v_pk_fma_f32 v[0:1], v[0:1], v[42:43], v[120:121] op_sel_hi:[1,0,1]
	v_pk_fma_f32 v[6:7], v[6:7], v[42:43], v[126:127] op_sel_hi:[1,0,1]
	v_pk_fma_f32 v[4:5], v[4:5], v[42:43], v[124:125] op_sel_hi:[1,0,1]
	v_pk_fma_f32 v[10:11], v[10:11], v[42:43], v[130:131] op_sel_hi:[1,0,1]
	v_pk_fma_f32 v[8:9], v[8:9], v[42:43], v[128:129] op_sel_hi:[1,0,1]
	v_pk_fma_f32 v[14:15], v[14:15], v[42:43], v[134:135] op_sel_hi:[1,0,1]
	v_pk_fma_f32 v[12:13], v[12:13], v[42:43], v[132:133] op_sel_hi:[1,0,1]
	v_pk_fma_f32 v[18:19], v[18:19], v[42:43], v[138:139] op_sel_hi:[1,0,1]
	v_pk_fma_f32 v[16:17], v[16:17], v[42:43], v[136:137] op_sel_hi:[1,0,1]
	v_pk_fma_f32 v[22:23], v[22:23], v[42:43], v[142:143] op_sel_hi:[1,0,1]
	v_pk_fma_f32 v[20:21], v[20:21], v[42:43], v[140:141] op_sel_hi:[1,0,1]
	v_pk_fma_f32 v[26:27], v[26:27], v[42:43], v[146:147] op_sel_hi:[1,0,1]
	v_pk_fma_f32 v[24:25], v[24:25], v[42:43], v[144:145] op_sel_hi:[1,0,1]
	v_pk_fma_f32 v[30:31], v[30:31], v[42:43], v[150:151] op_sel_hi:[1,0,1]
	v_pk_fma_f32 v[28:29], v[28:29], v[42:43], v[148:149] op_sel_hi:[1,0,1]
	s_cmp_lg_u32 s98, 0
	s_cbranch_scc0 .Lpff_lastB
	s_add_u32 s26, s92, s23
	s_addc_u32 s27, s93, s24
	global_load_dword v162, v81, s[26:27]
	s_mov_b32 s25, 0x1b000000
	s_add_i32 s22, s22, -1
	s_add_u32 s23, s23, 4
	s_addc_u32 s24, s24, 0
	s_cmp_eq_u32 s22, 0
	s_cselect_b32 s98, 0, 1
	v_lshl_add_u64 v[38:39], s[92:93], 0, v[34:35]
	v_add_co_u32_e32 v44, vcc, s25, v38
	s_mov_b32 s25, 0x1b001000
	s_nop 0
	v_addc_co_u32_e32 v45, vcc, 0, v39, vcc
	v_add_co_u32_e32 v46, vcc, s25, v38
	v_lshl_add_u64 v[34:35], v[34:35], 0, s[14:15]
	s_nop 0
	v_addc_co_u32_e32 v47, vcc, 0, v39, vcc
	global_load_dwordx4 v[120:123], v[46:47], off offset:-4096
	global_load_dwordx4 v[124:127], v[44:45], off offset:1024
	global_load_dwordx4 v[128:131], v[44:45], off offset:2048
	global_load_dwordx4 v[132:135], v[44:45], off offset:3072
	global_load_dwordx4 v[136:139], v[46:47], off
	global_load_dwordx4 v[140:143], v[46:47], off offset:1024
	global_load_dwordx4 v[144:147], v[46:47], off offset:2048
	global_load_dwordx4 v[148:151], v[46:47], off offset:3072
	s_waitcnt vmcnt(17)
	v_mul_f32_e32 v206, 0x3fb8aa3b, v206
	v_exp_f32_e32 v42, v206
	s_waitcnt vmcnt(9)
	v_pk_fma_f32 v[2:3], v[2:3], v[42:43], v[192:193] op_sel_hi:[1,0,1]
	v_pk_fma_f32 v[0:1], v[0:1], v[42:43], v[190:191] op_sel_hi:[1,0,1]
	v_pk_fma_f32 v[6:7], v[6:7], v[42:43], v[196:197] op_sel_hi:[1,0,1]
	v_pk_fma_f32 v[4:5], v[4:5], v[42:43], v[194:195] op_sel_hi:[1,0,1]
	v_pk_fma_f32 v[10:11], v[10:11], v[42:43], v[200:201] op_sel_hi:[1,0,1]
	v_pk_fma_f32 v[8:9], v[8:9], v[42:43], v[198:199] op_sel_hi:[1,0,1]
	v_pk_fma_f32 v[14:15], v[14:15], v[42:43], v[204:205] op_sel_hi:[1,0,1]
	v_pk_fma_f32 v[12:13], v[12:13], v[42:43], v[202:203] op_sel_hi:[1,0,1]
	v_pk_fma_f32 v[18:19], v[18:19], v[42:43], v[238:239] op_sel_hi:[1,0,1]
	v_pk_fma_f32 v[16:17], v[16:17], v[42:43], v[236:237] op_sel_hi:[1,0,1]
	v_pk_fma_f32 v[22:23], v[22:23], v[42:43], v[242:243] op_sel_hi:[1,0,1]
	v_pk_fma_f32 v[20:21], v[20:21], v[42:43], v[240:241] op_sel_hi:[1,0,1]
	v_pk_fma_f32 v[26:27], v[26:27], v[42:43], v[246:247] op_sel_hi:[1,0,1]
	v_pk_fma_f32 v[24:25], v[24:25], v[42:43], v[244:245] op_sel_hi:[1,0,1]
	v_pk_fma_f32 v[30:31], v[30:31], v[42:43], v[250:251] op_sel_hi:[1,0,1]
	v_pk_fma_f32 v[28:29], v[28:29], v[42:43], v[248:249] op_sel_hi:[1,0,1]
	s_branch .Lpff_loop

; template <int PASS>
; __device__ void ssd_item(const Params& p, int item, int l, unsigned char* smem) {
;     ...
;     f32x4 S[8];
; #pragma unroll
;     for (int nt = 0; nt < 8; ++nt) S[nt] = (f32x4){0.f, 0.f, 0.f, 0.f};
;     const int ibase = item & ~15;
;     if (PASS == 3) {
;         if (dir == 0) {
;             for (int e = 0; e < seg; ++e) { const float dc = __expf(SEGT[ibase + e]); const f32x4* src = (const f32x4*)(ST + (size_t)(ibase + e) * 8192);
; #pragma unroll
;                 for (int nt = 0; nt < 8; ++nt) S[nt] = S[nt] * dc + src[(w * 8 + nt) * 64 + lane]; }
;         } else {
;             for (int e = NSEG - 1; e > seg; --e) { const float dc = __expf(SEGT[ibase + e]); const f32x4* src = (const f32x4*)(ST + (size_t)(ibase + e) * 8192);
; #pragma unroll
;                 for (int nt = 0; nt < 8; ++nt) S[nt] = S[nt] * dc + src[(w * 8 + nt) * 64 + lane]; }
;         }
.Lpff_done:
	s_branch .LBB0_868
.LBB0_866:
	v_mov_b32_e32 v80, v81
	v_mov_b32_e32 v82, v81
	v_mov_b32_e32 v83, v81
	v_mov_b64_e32 v[28:29], v[80:81]
	s_waitcnt vmcnt(4)
	v_mov_b64_e32 v[24:25], v[80:81]
	v_mov_b64_e32 v[20:21], v[80:81]
	v_mov_b64_e32 v[16:17], v[80:81]
	v_mov_b64_e32 v[12:13], v[80:81]
	v_mov_b64_e32 v[8:9], v[80:81]
	v_mov_b64_e32 v[4:5], v[80:81]
	v_mov_b64_e32 v[0:1], v[80:81]
	v_mov_b64_e32 v[30:31], v[82:83]
	v_mov_b64_e32 v[26:27], v[82:83]
	v_mov_b64_e32 v[22:23], v[82:83]
	v_mov_b64_e32 v[18:19], v[82:83]
	v_mov_b64_e32 v[14:15], v[82:83]
	v_mov_b64_e32 v[10:11], v[82:83]
	v_mov_b64_e32 v[6:7], v[82:83]
	v_mov_b64_e32 v[2:3], v[82:83]
	s_cbranch_execz .LBB0_863
	s_branch .LBB0_868
